# v27 plus gain-vector loads hoisted out of ph_post and rmsnorm_b16 row loops
# speedup vs baseline: 1.0316x; 1.0048x over previous
; __device__ __forceinline__ unsigned cvt_pk_bf16(float lo, float hi) { unsigned r; asm volatile("v_cvt_pk_bf16_f32 %0, %1, %2" : "=v"(r) : "v"(lo), "v"(hi)); return r; }
; __device__ __forceinline__ int otid() { int t = threadIdx.x; asm volatile("" : "+v"(t)); return t; }
; __device__ __forceinline__ uint4 ntld_u4(const void* p) { const ntu4_t v = __builtin_nontemporal_load((const ntu4_t*)p); return make_uint4(v.x, v.y, v.z, v.w); }
; __device__ void ph_rmsnorm_rows_b16(const bf16_t* __restrict__ hb, const float* __restrict__ g, bf16_t* __restrict__ out) {
;     const int tid = otid(); const int lane = tid & 63, wid = tid >> 6;
;     for (int row = blockIdx.x * 8 + wid; row < T_TOK; row += gridDim.x * 8) {
;         const size_t ro = (size_t)row * DM; uint4 w[2]; float v[2][8]; float ss = 0.f;
; #pragma unroll
;         for (int i = 0; i < 2; ++i) w[i] = ntld_u4(hb + ro + (lane + 64 * i) * 8);
; #pragma unroll
;         for (int i = 0; i < 2; ++i) { const unsigned ww[4] = {w[i].x, w[i].y, w[i].z, w[i].w};
; #pragma unroll
;             for (int k = 0; k < 4; ++k) { v[i][2 * k] = __uint_as_float(ww[k] << 16); v[i][2 * k + 1] = __uint_as_float(ww[k] & 0xffff0000u); ss += v[i][2 * k] * v[i][2 * k] + v[i][2 * k + 1] * v[i][2 * k + 1]; } }
;         ss = wave_sum(ss);
;         const float r = rsqrtf(ss * (1.0f / DM) + RMS_EPS);
;         float4 gaa[2], gbb[2];
; #pragma unroll
;         for (int i = 0; i < 2; ++i) { const int e0 = (lane + 64 * i) * 8; gaa[i] = *(const float4*)(g + e0); gbb[i] = *(const float4*)(g + e0 + 4); }
; #pragma unroll
;         for (int i = 0; i < 2; ++i) { const int e0 = (lane + 64 * i) * 8; const float4 ga = gaa[i], gb = gbb[i];
;             uint4 o; o.x = pg8::cvt_pk_bf16(v[i][0] * r * ga.x, v[i][1] * r * ga.y); o.y = pg8::cvt_pk_bf16(v[i][2] * r * ga.z, v[i][3] * r * ga.w);
;             o.z = pg8::cvt_pk_bf16(v[i][4] * r * gb.x, v[i][5] * r * gb.y); o.w = pg8::cvt_pk_bf16(v[i][6] * r * gb.z, v[i][7] * r * gb.w);
;             *(uint4*)(out + ro + e0) = o; }
;     }
.LBB0_11:
	s_lshr_b32 s6, s28, 1
	v_writelane_b32 v255, s6, 50
	s_lshr_b64 s[30:31], s[28:29], 1
	s_andn2_b64 vcc, exec, s[10:11]
	v_writelane_b32 v255, s7, 51
	v_readlane_b32 s6, v252, 58
	v_writelane_b32 v255, s28, 52
	v_readlane_b32 s7, v252, 59
	s_nop 0
	v_writelane_b32 v255, s29, 53
	s_cbranch_vccnz .LBB0_149
	s_cmp_lg_u32 s28, 0
	s_cbranch_scc0 .LBB0_17
	s_waitcnt vmcnt(0)
	v_mov_b32_e32 v1, v195
	v_readlane_b32 s0, v252, 52
	v_ashrrev_i32_e32 v0, 6, v1
	s_nop 0
	v_add_u32_e32 v0, s0, v0
	s_mov_b32 s0, 0x8000
	v_cmp_gt_i32_e32 vcc, s0, v0
	s_and_saveexec_b64 s[14:15], vcc
	s_cbranch_execz .LBB0_16
	s_lshl_b32 s62, s28, 10
	v_readlane_b32 s40, v252, 2
	s_lshl_b64 s[0:1], s[62:63], 2
	v_readlane_b32 s48, v252, 10
	v_lshlrev_b32_e32 v1, 3, v1
	v_readlane_b32 s49, v252, 11
	s_add_u32 s0, s48, s0
	v_and_b32_e32 v1, 0x1f8, v1
	s_addc_u32 s1, s49, s1
	v_lshlrev_b32_e32 v192, 2, v1
	v_readlane_b32 s28, v255, 52
	v_lshl_add_u64 v[2:3], s[0:1], 0, v[192:193]
	v_lshlrev_b32_e32 v192, 1, v1
	v_readlane_b32 s29, v255, 53
	v_readlane_b32 s6, v252, 53
	v_lshl_add_u64 v[4:5], s[76:77], 0, v[192:193]
	v_lshl_add_u64 v[6:7], s[78:79], 0, v[192:193]
	s_mov_b64 s[10:11], 0
	v_readlane_b32 s41, v252, 3
	v_readlane_b32 s42, v252, 4
	v_readlane_b32 s43, v252, 5
	v_readlane_b32 s44, v252, 6
	v_readlane_b32 s45, v252, 7
	v_readlane_b32 s46, v252, 8
	v_readlane_b32 s47, v252, 9
	v_readlane_b32 s50, v252, 12
	v_readlane_b32 s51, v252, 13
	v_readlane_b32 s52, v252, 14
	v_readlane_b32 s53, v252, 15
	v_readlane_b32 s54, v252, 16
	v_readlane_b32 s55, v252, 17
	global_load_dwordx4 v[104:107], v[2:3], off offset:16
	global_load_dwordx4 v[108:111], v[2:3], off
	global_load_dwordx4 v[112:115], v[2:3], off offset:2064
	global_load_dwordx4 v[116:119], v[2:3], off offset:2048
.LBB0_15:
	v_ashrrev_i32_e32 v1, 31, v0
	v_lshlrev_b64 v[32:33], 11, v[0:1]
	v_lshl_add_u64 v[12:13], v[4:5], 0, v[32:33]
	global_load_dwordx4 v[8:11], v[12:13], off nt
	s_nop 0
	global_load_dwordx4 v[12:15], v[12:13], off offset:1024 nt
	v_mov_b32_e32 v1, v239
	v_lshlrev_b32_e32 v1, 2, v1
	v_xor_b32_e32 v38, 0x80, v1
	v_add_u32_e32 v0, s6, v0
	v_cmp_lt_i32_e64 s[38:39], s33, v0
	v_lshl_add_u64 v[32:33], v[6:7], 0, v[32:33]
	s_or_b64 s[10:11], s[38:39], s[10:11]
	s_waitcnt vmcnt(1)
	v_and_b32_e32 v40, 0xffff0000, v8
	v_and_b32_e32 v42, 0xffff0000, v9
	v_lshlrev_b32_e32 v39, 16, v8
	v_lshlrev_b32_e32 v41, 16, v9
	v_and_b32_e32 v44, 0xffff0000, v10
	v_mul_f32_e32 v47, v40, v40
	v_mul_f32_e32 v48, v42, v42
	v_lshlrev_b32_e32 v43, 16, v10
	v_and_b32_e32 v46, 0xffff0000, v11
	v_mul_f32_e32 v49, v44, v44
	v_fmac_f32_e32 v47, v39, v39
	v_fmac_f32_e32 v48, v41, v41
	v_lshlrev_b32_e32 v45, 16, v11
	s_waitcnt vmcnt(0)
	v_and_b32_e32 v11, 0xffff0000, v13
	v_and_b32_e32 v10, 0xffff0000, v12
	v_mul_f32_e32 v50, v46, v46
	v_fmac_f32_e32 v49, v43, v43
	v_add_f32_e32 v47, v47, v48
	v_lshlrev_b32_e32 v9, 16, v13
	v_lshlrev_b32_e32 v8, 16, v12
	v_pk_mul_f32 v[34:35], v[10:11], v[10:11]
	v_fmac_f32_e32 v50, v45, v45
	v_add_f32_e32 v47, v49, v47
	v_lshlrev_b32_e32 v13, 16, v15
	v_lshlrev_b32_e32 v12, 16, v14
	v_and_b32_e32 v15, 0xffff0000, v15
	v_and_b32_e32 v14, 0xffff0000, v14
	v_pk_fma_f32 v[34:35], v[8:9], v[8:9], v[34:35]
	v_add_f32_e32 v47, v50, v47
	v_pk_mul_f32 v[36:37], v[14:15], v[14:15]
	v_add_f32_e32 v34, v34, v47
	v_pk_fma_f32 v[36:37], v[12:13], v[12:13], v[36:37]
	v_add_f32_e32 v34, v35, v34
	v_add_f32_e32 v34, v36, v34
	v_add_f32_e32 v34, v37, v34
	ds_bpermute_b32 v35, v38, v34
	v_xor_b32_e32 v36, 64, v1
	s_waitcnt lgkmcnt(0)
	v_add_f32_e32 v34, v34, v35
	ds_bpermute_b32 v35, v36, v34
	v_xor_b32_e32 v36, 32, v1
	s_waitcnt lgkmcnt(0)
	v_add_f32_e32 v34, v34, v35
	ds_bpermute_b32 v35, v36, v34
	v_xor_b32_e32 v36, 16, v1
	s_waitcnt lgkmcnt(0)
	v_add_f32_e32 v34, v34, v35
	ds_bpermute_b32 v35, v36, v34
	v_xor_b32_e32 v36, 8, v1
	v_xor_b32_e32 v1, 4, v1
	s_waitcnt lgkmcnt(0)
	v_add_f32_e32 v34, v34, v35
	ds_bpermute_b32 v35, v36, v34
	s_waitcnt lgkmcnt(0)
	v_add_f32_e32 v34, v34, v35
	ds_bpermute_b32 v1, v1, v34
	s_waitcnt lgkmcnt(0)
	v_add_f32_e32 v1, v34, v1
	v_fmamk_f32 v1, v1, 0x3a800000, v194
	v_mul_f32_e32 v34, 0x4b800000, v1
	v_cmp_gt_f32_e32 vcc, s23, v1
	s_nop 1
	v_cndmask_b32_e32 v1, v1, v34, vcc
	v_rsq_f32_e32 v1, v1
	s_nop 0
	v_mul_f32_e32 v34, 0x45800000, v1
	v_cndmask_b32_e32 v1, v1, v34, vcc
	v_mul_f32_e32 v34, v1, v39
	v_mul_f32_e32 v35, v1, v40
	v_mul_f32_e32 v36, v1, v41
	v_mul_f32_e32 v37, v1, v42
	v_mul_f32_e32 v38, v1, v43
	v_mul_f32_e32 v39, v1, v44
	v_mul_f32_e32 v40, v1, v45
	v_mul_f32_e32 v41, v1, v46
	v_mul_f32_e32 v8, v1, v8
	v_mul_f32_e32 v10, v1, v10
	v_mul_f32_e32 v9, v1, v9
	v_mul_f32_e32 v11, v1, v11
	v_mul_f32_e32 v12, v1, v12
	v_mul_f32_e32 v14, v1, v14
	v_mul_f32_e32 v13, v1, v13
	v_mul_f32_e32 v1, v1, v15
	v_mul_f32_e32 v15, v108, v34
	v_mul_f32_e32 v20, v109, v35
	v_mul_f32_e32 v21, v110, v36
	v_mul_f32_e32 v22, v111, v37
	v_mul_f32_e32 v16, v104, v38
	v_mul_f32_e32 v17, v105, v39
	v_mul_f32_e32 v18, v106, v40
	v_mul_f32_e32 v19, v107, v41
	v_mul_f32_e32 v23, v116, v8
	v_mul_f32_e32 v28, v117, v10
	v_mul_f32_e32 v29, v118, v9
	v_mul_f32_e32 v30, v119, v11
	v_cvt_pk_bf16_f32 v8, v15, v20
	v_cvt_pk_bf16_f32 v9, v21, v22
	v_cvt_pk_bf16_f32 v10, v16, v17
	v_cvt_pk_bf16_f32 v11, v18, v19
	v_mul_f32_e32 v12, v112, v12
	v_mul_f32_e32 v14, v113, v14
	v_mul_f32_e32 v13, v114, v13
	v_mul_f32_e32 v1, v115, v1
	global_store_dwordx4 v[32:33], v[8:11], off
	s_nop 1
	v_cvt_pk_bf16_f32 v8, v23, v28
	v_cvt_pk_bf16_f32 v9, v29, v30
	v_cvt_pk_bf16_f32 v10, v12, v14
	v_cvt_pk_bf16_f32 v11, v13, v1
	global_store_dwordx4 v[32:33], v[8:11], off offset:1024
	s_andn2_b64 exec, exec, s[10:11]
	s_cbranch_execnz .LBB0_15

; __device__ __forceinline__ int otid() { int t = threadIdx.x; asm volatile("" : "+v"(t)); return t; }
; __device__ __forceinline__ uint4 ntld_u4(const void* p) { const ntu4_t v = __builtin_nontemporal_load((const ntu4_t*)p); return make_uint4(v.x, v.y, v.z, v.w); }
; __device__ __forceinline__ float4 ntld_f4(const void* p) { const ntf4_t v = __builtin_nontemporal_load((const ntf4_t*)p); return make_float4(v.x, v.y, v.z, v.w); }
; __device__ void ph_post(const float* hin_f, const bf16_t* hin_b, const bf16_t* t1, const float* gpost, bf16_t* E, const float* gple, bf16_t* h1b) {
;     const int tid = otid(); const int lane = tid & 63, wid = tid >> 6;
;     for (int row = blockIdx.x * 8 + wid; row < T_TOK; row += gridDim.x * 8) {
;         const size_t ro = (size_t)row * DM;
;         uint4 tw[2], ew[2]; float hv[2][8];
; #pragma unroll
;         for (int i = 0; i < 2; ++i) { const int e0 = (lane + 64 * i) * 8; tw[i] = ntld_u4(t1 + ro + e0); ew[i] = ntld_u4(E + ro + e0); }
;         if (hin_b) {
; #pragma unroll
;             for (int i = 0; i < 2; ++i) { const uint4 hw = ntld_u4(hin_b + ro + (lane + 64 * i) * 8); unpack8(hw, hv[i]); }
;         } else {
; #pragma unroll
;             for (int i = 0; i < 2; ++i) { const int e0 = (lane + 64 * i) * 8; const float4 a = ntld_f4(hin_f + ro + e0), b = ntld_f4(hin_f + ro + e0 + 4);
;                 hv[i][0] = a.x; hv[i][1] = a.y; hv[i][2] = a.z; hv[i][3] = a.w; hv[i][4] = b.x; hv[i][5] = b.y; hv[i][6] = b.z; hv[i][7] = b.w; } }
;         float tv[2][8], ev[2][8]; float ss = 0.f, se = 0.f;
; #pragma unroll
;         for (int i = 0; i < 2; ++i) { unpack8(tw[i], tv[i]); unpack8(ew[i], ev[i]);
; #pragma unroll
;             for (int k = 0; k < 8; ++k) { ss += tv[i][k] * tv[i][k]; se += ev[i][k] * ev[i][k]; } }
;         ss = wave_sum(ss); se = wave_sum(se);
;         const float r = rsqrtf(ss * (1.0f / DM) + RMS_EPS), re = rsqrtf(se * (1.0f / DM) + RMS_EPS);
;         float4 gaa[2], gbb[2], paa[2], pbb[2];
; #pragma unroll
;         for (int i = 0; i < 2; ++i) { const int e0 = (lane + 64 * i) * 8; gaa[i] = *(const float4*)(gpost + e0); gbb[i] = *(const float4*)(gpost + e0 + 4); paa[i] = *(const float4*)(gple + e0); pbb[i] = *(const float4*)(gple + e0 + 4); }
.LBB0_765:
	s_andn2_b64 vcc, exec, s[6:7]
	s_cbranch_vccnz .LBB0_840
	s_waitcnt vmcnt(0)
	v_mov_b32_e32 v0, v195
	v_readlane_b32 s0, v252, 52
	v_ashrrev_i32_e32 v1, 6, v0
	s_nop 0
	v_add_u32_e32 v36, s0, v1
	s_mov_b32 s0, 0x8000
	v_cmp_gt_i32_e32 vcc, s0, v36
	s_and_saveexec_b64 s[6:7], vcc
	s_cbranch_execz .LBB0_773
	s_cmp_lg_u32 s28, 0
	s_cselect_b32 s1, s77, 0
	s_cselect_b32 s0, s76, 0
	s_lshl_b32 s62, s28, 10
	s_lshl_b64 s[10:11], s[62:63], 2
	s_add_u32 s24, s72, s10
	v_readlane_b32 s40, v252, 2
	s_addc_u32 s25, s73, s11
	v_readlane_b32 s50, v252, 12
	v_lshlrev_b32_e32 v0, 3, v0
	v_readlane_b32 s51, v252, 13
	s_add_u32 s10, s50, s10
	v_and_b32_e32 v0, 0x1f8, v0
	s_addc_u32 s11, s51, s11
	v_lshlrev_b32_e32 v192, 2, v0
	v_lshl_add_u64 v[38:39], s[10:11], 0, v[192:193]
	v_readlane_b32 s10, v252, 36
	v_lshlrev_b32_e32 v0, 1, v0
	v_mov_b32_e32 v1, v193
	v_readlane_b32 s11, v252, 37
	v_readlane_b32 s41, v252, 3
	v_readlane_b32 s28, v255, 52
	v_lshl_add_u64 v[42:43], s[10:11], 0, v[0:1]
	v_readlane_b32 s10, v252, 38
	s_cmp_lg_u64 s[0:1], 0
	v_readlane_b32 s11, v252, 39
	v_readlane_b32 s29, v255, 53
	v_readlane_b32 s12, v252, 53
	s_mov_b64 s[14:15], 0
	s_cselect_b64 s[30:31], -1, 0
	v_lshl_add_u64 v[40:41], s[24:25], 0, v[192:193]
	v_lshl_add_u64 v[44:45], s[10:11], 0, v[0:1]
	v_lshl_add_u64 v[46:47], s[0:1], 0, v[0:1]
	v_lshl_add_u64 v[48:49], s[40:41], 0, v[192:193]
	v_lshl_add_u64 v[50:51], s[78:79], 0, v[0:1]
	v_readlane_b32 s42, v252, 4
	v_readlane_b32 s43, v252, 5
	v_readlane_b32 s44, v252, 6
	v_readlane_b32 s45, v252, 7
	v_readlane_b32 s46, v252, 8
	v_readlane_b32 s47, v252, 9
	v_readlane_b32 s48, v252, 10
	v_readlane_b32 s49, v252, 11
	v_readlane_b32 s52, v252, 14
	v_readlane_b32 s53, v252, 15
	v_readlane_b32 s54, v252, 16
	v_readlane_b32 s55, v252, 17
	global_load_dwordx4 v[104:107], v[38:39], off offset:16
	global_load_dwordx4 v[108:111], v[38:39], off
	global_load_dwordx4 v[112:115], v[40:41], off offset:16
	global_load_dwordx4 v[116:119], v[40:41], off
	global_load_dwordx4 v[120:123], v[38:39], off offset:2064
	global_load_dwordx4 v[124:127], v[38:39], off offset:2048
	global_load_dwordx4 v[128:131], v[40:41], off offset:2064
	global_load_dwordx4 v[132:135], v[40:41], off offset:2048
	s_branch .LBB0_770

; __device__ __forceinline__ unsigned cvt_pk_bf16(float lo, float hi) { unsigned r; asm volatile("v_cvt_pk_bf16_f32 %0, %1, %2" : "=v"(r) : "v"(lo), "v"(hi)); return r; }
; __device__ void ph_post(const float* hin_f, const bf16_t* hin_b, const bf16_t* t1, const float* gpost, bf16_t* E, const float* gple, bf16_t* h1b) {
;     ...
;         float tv[2][8], ev[2][8]; float ss = 0.f, se = 0.f;
; #pragma unroll
;         for (int i = 0; i < 2; ++i) { unpack8(tw[i], tv[i]); unpack8(ew[i], ev[i]);
; #pragma unroll
;             for (int k = 0; k < 8; ++k) { ss += tv[i][k] * tv[i][k]; se += ev[i][k] * ev[i][k]; } }
;         ss = wave_sum(ss); se = wave_sum(se);
;         const float r = rsqrtf(ss * (1.0f / DM) + RMS_EPS), re = rsqrtf(se * (1.0f / DM) + RMS_EPS);
;         float4 gaa[2], gbb[2], paa[2], pbb[2];
; #pragma unroll
;         for (int i = 0; i < 2; ++i) { const int e0 = (lane + 64 * i) * 8; gaa[i] = *(const float4*)(gpost + e0); gbb[i] = *(const float4*)(gpost + e0 + 4); paa[i] = *(const float4*)(gple + e0); pbb[i] = *(const float4*)(gple + e0 + 4); }
; #pragma unroll
;         for (int i = 0; i < 2; ++i) { const int e0 = (lane + 64 * i) * 8;
;             const float4 ga = gaa[i], gb = gbb[i], pa = paa[i], pb = pbb[i];
;             const float gg[8] = {ga.x, ga.y, ga.z, ga.w, gb.x, gb.y, gb.z, gb.w}, pp[8] = {pa.x, pa.y, pa.z, pa.w, pb.x, pb.y, pb.z, pb.w};
;             float o[8], x[8];
; #pragma unroll
;             for (int k = 0; k < 8; ++k) { o[k] = hv[i][k] + tv[i][k] * r * gg[k]; x[k] = ev[i][k] * re * pp[k]; }
;             uint4 w; w.x = pg8::cvt_pk_bf16(o[0], o[1]); w.y = pg8::cvt_pk_bf16(o[2], o[3]); w.z = pg8::cvt_pk_bf16(o[4], o[5]); w.w = pg8::cvt_pk_bf16(o[6], o[7]);
;             *(uint4*)(h1b + ro + e0) = w;
;             uint4 xx; xx.x = pg8::cvt_pk_bf16(x[0], x[1]); xx.y = pg8::cvt_pk_bf16(x[2], x[3]); xx.z = pg8::cvt_pk_bf16(x[4], x[5]); xx.w = pg8::cvt_pk_bf16(x[6], x[7]);
;             *(uint4*)(E + ro + e0) = xx; }
;     }
.LBB0_769:
	s_waitcnt vmcnt(3)
	v_and_b32_e32 v85, 0xffff0000, v28
	s_waitcnt vmcnt(1)
	v_and_b32_e32 v84, 0xffff0000, v24
	v_lshlrev_b32_e32 v87, 16, v28
	v_lshlrev_b32_e32 v86, 16, v24
	v_lshlrev_b32_e32 v82, 16, v25
	v_and_b32_e32 v80, 0xffff0000, v25
	v_pk_mul_f32 v[24:25], v[84:85], v[84:85]
	v_lshlrev_b32_e32 v83, 16, v29
	v_pk_fma_f32 v[24:25], v[86:87], v[86:87], v[24:25]
	v_and_b32_e32 v81, 0xffff0000, v29
	v_lshlrev_b32_e32 v71, 16, v20
	v_and_b32_e32 v69, 0xffff0000, v20
	v_lshlrev_b32_e32 v67, 16, v21
	v_and_b32_e32 v63, 0xffff0000, v21
	v_pk_fma_f32 v[20:21], v[82:83], v[82:83], v[24:25]
	v_lshlrev_b32_e32 v79, 16, v30
	v_lshlrev_b32_e32 v78, 16, v26
	v_pk_fma_f32 v[20:21], v[80:81], v[80:81], v[20:21]
	v_and_b32_e32 v77, 0xffff0000, v30
	v_and_b32_e32 v76, 0xffff0000, v26
	v_pk_fma_f32 v[20:21], v[78:79], v[78:79], v[20:21]
	v_lshlrev_b32_e32 v75, 16, v31
	v_lshlrev_b32_e32 v74, 16, v27
	v_and_b32_e32 v60, 0xffff0000, v22
	v_lshlrev_b32_e32 v61, 16, v22
	v_pk_fma_f32 v[20:21], v[76:77], v[76:77], v[20:21]
	v_and_b32_e32 v73, 0xffff0000, v31
	v_and_b32_e32 v72, 0xffff0000, v27
	s_waitcnt vmcnt(0)
	v_lshlrev_b32_e32 v70, 16, v16
	v_and_b32_e32 v68, 0xffff0000, v16
	v_lshlrev_b32_e32 v66, 16, v17
	v_and_b32_e32 v62, 0xffff0000, v17
	v_pk_mul_f32 v[16:17], v[60:61], v[60:61]
	v_pk_fma_f32 v[20:21], v[74:75], v[74:75], v[20:21]
	v_and_b32_e32 v56, 0xffff0000, v23
	v_lshlrev_b32_e32 v57, 16, v23
	v_pk_fma_f32 v[20:21], v[72:73], v[72:73], v[20:21]
	v_mov_b32_e32 v23, v17
	v_mov_b32_e32 v17, v239
	v_pk_fma_f32 v[20:21], v[70:71], v[70:71], v[20:21]
	v_and_b32_e32 v64, 0xffff0000, v18
	v_lshlrev_b32_e32 v65, 16, v18
	v_pk_fma_f32 v[20:21], v[68:69], v[68:69], v[20:21]
	v_lshlrev_b32_e32 v17, 2, v17
	v_and_b32_e32 v58, 0xffff0000, v19
	v_lshlrev_b32_e32 v59, 16, v19
	v_pk_mul_f32 v[18:19], v[64:65], v[64:65]
	v_pk_fma_f32 v[20:21], v[66:67], v[66:67], v[20:21]
	v_xor_b32_e32 v26, 0x80, v17
	v_xor_b32_e32 v27, 64, v17
	v_xor_b32_e32 v28, 32, v17
	v_xor_b32_e32 v29, 16, v17
	v_xor_b32_e32 v30, 8, v17
	v_xor_b32_e32 v31, 4, v17
	v_mov_b32_e32 v17, v239
	v_pk_fma_f32 v[20:21], v[62:63], v[62:63], v[20:21]
	v_mov_b32_e32 v22, v19
	v_pk_add_f32 v[20:21], v[22:23], v[20:21]
	v_pk_mul_f32 v[22:23], v[56:57], v[56:57]
	v_pk_mul_f32 v[24:25], v[58:59], v[58:59]
	v_lshlrev_b32_e32 v17, 2, v17
	v_mov_b32_e32 v19, v16
	v_xor_b32_e32 v32, 0x80, v17
	v_xor_b32_e32 v33, 64, v17
	v_xor_b32_e32 v34, 32, v17
	v_xor_b32_e32 v35, 16, v17
	v_xor_b32_e32 v37, 8, v17
	v_xor_b32_e32 v88, 4, v17
	v_pk_add_f32 v[16:17], v[18:19], v[20:21]
	v_mov_b32_e32 v18, v25
	v_mov_b32_e32 v19, v23
	v_pk_add_f32 v[16:17], v[18:19], v[16:17]
	v_mov_b32_e32 v25, v22
	v_pk_add_f32 v[16:17], v[24:25], v[16:17]
	ds_bpermute_b32 v19, v26, v17
	ds_bpermute_b32 v18, v32, v16
	s_mov_b32 s0, 0x3a800000
	v_add_u32_e32 v36, s12, v36
	s_waitcnt lgkmcnt(0)
	v_pk_add_f32 v[16:17], v[16:17], v[18:19]
	ds_bpermute_b32 v19, v27, v17
	ds_bpermute_b32 v18, v33, v16
	s_waitcnt lgkmcnt(0)
	v_pk_add_f32 v[16:17], v[16:17], v[18:19]
	ds_bpermute_b32 v19, v28, v17
	ds_bpermute_b32 v18, v34, v16
	s_waitcnt lgkmcnt(0)
	v_pk_add_f32 v[16:17], v[16:17], v[18:19]
	ds_bpermute_b32 v19, v29, v17
	ds_bpermute_b32 v18, v35, v16
	s_waitcnt lgkmcnt(0)
	v_pk_add_f32 v[16:17], v[16:17], v[18:19]
	ds_bpermute_b32 v19, v30, v17
	ds_bpermute_b32 v18, v37, v16
	s_waitcnt lgkmcnt(0)
	v_pk_add_f32 v[16:17], v[16:17], v[18:19]
	ds_bpermute_b32 v19, v31, v17
	ds_bpermute_b32 v18, v88, v16
	s_waitcnt lgkmcnt(0)
	v_pk_add_f32 v[16:17], v[16:17], v[18:19]
	s_nop 0
	v_pk_fma_f32 v[16:17], v[16:17], s[0:1], v[194:195] op_sel_hi:[1,0,0]
	s_nop 0
	v_mul_f32_e32 v18, 0x4b800000, v17
	v_cmp_gt_f32_e64 s[38:39], s23, v17
	v_cmp_gt_f32_e32 vcc, s23, v16
	s_nop 0
	v_cndmask_b32_e64 v17, v17, v18, s[38:39]
	v_rsq_f32_e32 v37, v17
	v_mul_f32_e32 v17, 0x4b800000, v16
	v_cndmask_b32_e32 v16, v16, v17, vcc
	v_rsq_f32_e32 v101, v16
	v_mul_f32_e32 v100, 0x45800000, v37
	v_cndmask_b32_e64 v37, v37, v100, s[38:39]
	v_mul_f32_e32 v102, 0x45800000, v101
	v_cndmask_b32_e32 v100, v101, v102, vcc
	v_mul_f32_e32 v87, v37, v87
	v_cmp_lt_i32_e32 vcc, s33, v36
	s_or_b64 s[14:15], vcc, s[14:15]
	v_fmac_f32_e32 v8, v108, v87
	v_mul_f32_e32 v28, v100, v86
	v_mul_f32_e32 v28, v116, v28
	v_mul_f32_e32 v32, v37, v85
	v_fmac_f32_e32 v9, v109, v32
	v_mul_f32_e32 v32, v37, v83
	v_fmac_f32_e32 v10, v32, v110
	v_mul_f32_e32 v32, v37, v81
	v_fmac_f32_e32 v11, v32, v111
	v_mul_f32_e32 v32, v37, v79
	v_fmac_f32_e32 v12, v32, v104
	v_mul_f32_e32 v16, v100, v78
	v_mul_f32_e32 v16, v16, v112
	v_mul_f32_e32 v24, v37, v77
	v_fmac_f32_e32 v13, v24, v105
	v_mul_f32_e32 v24, v37, v75
	v_fmac_f32_e32 v14, v24, v106
	v_mul_f32_e32 v24, v37, v73
	v_mul_f32_e32 v29, v100, v84
	v_mul_f32_e32 v30, v100, v82
	v_mul_f32_e32 v31, v100, v80
	v_mul_f32_e32 v17, v100, v76
	v_mul_f32_e32 v18, v100, v74
	v_fmac_f32_e32 v15, v24, v107
	v_mul_f32_e32 v19, v100, v72
	v_cvt_pk_bf16_f32 v8, v8, v9
	v_cvt_pk_bf16_f32 v9, v10, v11
	v_cvt_pk_bf16_f32 v10, v12, v13
	v_cvt_pk_bf16_f32 v11, v14, v15
	v_lshl_add_u64 v[12:13], v[54:55], 1, v[50:51]
	v_mul_f32_e32 v29, v29, v117
	v_mul_f32_e32 v30, v30, v118
	v_mul_f32_e32 v31, v31, v119
	v_mul_f32_e32 v17, v17, v113
	v_mul_f32_e32 v18, v18, v114
	v_mul_f32_e32 v19, v19, v115
	global_store_dwordx4 v[12:13], v[8:11], off
	v_mul_f32_e32 v14, v37, v61
	v_mul_f32_e32 v15, v37, v60
	v_cvt_pk_bf16_f32 v8, v28, v29
	v_cvt_pk_bf16_f32 v9, v30, v31
	v_cvt_pk_bf16_f32 v10, v16, v17
	v_cvt_pk_bf16_f32 v11, v18, v19
	global_store_dwordx4 v[52:53], v[8:11], off
	v_mul_f32_e32 v16, v37, v57
	v_mul_f32_e32 v17, v37, v56
	v_mul_f32_e32 v8, v37, v71
	v_mul_f32_e32 v9, v37, v69
	v_mul_f32_e32 v10, v37, v67
	v_mul_f32_e32 v11, v37, v63
	v_fmac_f32_e32 v0, v8, v124
	v_fmac_f32_e32 v1, v9, v125
	v_fmac_f32_e32 v2, v10, v126
	v_fmac_f32_e32 v3, v11, v127
	v_mul_f32_e32 v8, v100, v70
	v_mul_f32_e32 v9, v100, v68
	v_mul_f32_e32 v10, v100, v66
	v_mul_f32_e32 v11, v100, v62
	v_fmac_f32_e32 v4, v14, v120
	v_mul_f32_e32 v14, v100, v65
	v_fmac_f32_e32 v5, v15, v121
	v_mul_f32_e32 v15, v100, v64
	v_fmac_f32_e32 v6, v16, v122
	v_mul_f32_e32 v16, v100, v59
	v_fmac_f32_e32 v7, v17, v123
	v_mul_f32_e32 v17, v100, v58
	v_cvt_pk_bf16_f32 v0, v0, v1
	v_cvt_pk_bf16_f32 v1, v2, v3
	v_cvt_pk_bf16_f32 v2, v4, v5
	v_cvt_pk_bf16_f32 v3, v6, v7
	v_mul_f32_e32 v8, v8, v132
	v_mul_f32_e32 v9, v9, v133
	v_mul_f32_e32 v10, v10, v134
	v_mul_f32_e32 v11, v11, v135
	v_mul_f32_e32 v14, v14, v128
	v_mul_f32_e32 v15, v15, v129
	v_mul_f32_e32 v16, v16, v130
	v_mul_f32_e32 v17, v17, v131
	global_store_dwordx4 v[12:13], v[0:3], off offset:1024
	s_nop 1
	v_cvt_pk_bf16_f32 v0, v8, v9
	v_cvt_pk_bf16_f32 v1, v10, v11
	v_cvt_pk_bf16_f32 v2, v14, v15
	v_cvt_pk_bf16_f32 v3, v16, v17
	global_store_dwordx4 v[52:53], v[0:3], off offset:1024
	s_andn2_b64 exec, exec, s[14:15]
	s_cbranch_execz .LBB0_773
